# residual-stream stores: sc1 nt (write-through + streaming) instead of nt
# speedup vs baseline: 1.0111x; 1.0111x over previous
; __device__ __forceinline__ void st16_wt(void* p, u32x4 v) { asm volatile("global_store_dwordx4 %0, %1, off sc1\n\ts_nop 4" :: "v"(p), "v"(v) : "memory"); }
; __device__ __forceinline__ void resnorm_rows(const float* hin, const bf16_t* tmp, const float* g1, float* hout, const float* g2, bf16_t* xn, int gw, int NGW, int lane) {
;     ...
;         const u32x2* tr = (const u32x2*)(tmp + (size_t)row * DMODEL) + lane; f32x4 t[4]; float ss = 0.f;
; #pragma unroll
;         for (int j = 0; j < 4; ++j) { const u32x2 w = __builtin_nontemporal_load(tr + 64 * j); t[j] = (f32x4){bflo(w.x), bfhi(w.x), bflo(w.y), bfhi(w.y)}; ss += (t[j][0] * t[j][0] + t[j][1] * t[j][1]) + (t[j][2] * t[j][2] + t[j][3] * t[j][3]); }
;         const float rs = __builtin_amdgcn_rsqf(wave_sum(ss) * (1.f / DMODEL) + EPSN);
;         const f32x4* hr = (const f32x4*)(hin + (size_t)row * DMODEL) + lane; f32x4* ho = (f32x4*)(hout + (size_t)row * DMODEL) + lane; float s2 = 0.f;
; #pragma unroll
;         for (int j = 0; j < 4; ++j) { const f32x4 gg = ((const f32x4*)g1)[lane + 64 * j]; f32x4 h = __builtin_nontemporal_load(hr + 64 * j);
;             h[0] += t[j][0] * rs * gg[0]; h[1] += t[j][1] * rs * gg[1]; h[2] += t[j][2] * rs * gg[2]; h[3] += t[j][3] * rs * gg[3];
;             st16_wt(ho + 64 * j, __builtin_bit_cast(u32x4, h)); t[j] = h; s2 += (h[0] * h[0] + h[1] * h[1]) + (h[2] * h[2] + h[3] * h[3]); }
.Lrn_nopf_ph7:
	v_and_b32_e32 v35, 0xffff0000, v11
	v_and_b32_e32 v37, 0xffff0000, v10
	v_lshlrev_b32_e32 v34, 16, v11
	v_lshlrev_b32_e32 v36, 16, v10
	v_lshlrev_b32_e32 v41, 16, v13
	v_lshlrev_b32_e32 v40, 16, v12
	v_and_b32_e32 v43, 0xffff0000, v13
	v_and_b32_e32 v42, 0xffff0000, v12
	v_mov_b32_e32 v12, v37
	v_mov_b32_e32 v13, v35
	v_lshlrev_b32_e32 v44, 16, v23
	v_and_b32_e32 v45, 0xffff0000, v23
	v_lshlrev_b32_e32 v46, 16, v22
	v_and_b32_e32 v47, 0xffff0000, v22
	v_mov_b32_e32 v10, v36
	v_mov_b32_e32 v11, v34
	v_pk_mul_f32 v[22:23], v[42:43], v[42:43]
	v_pk_mul_f32 v[12:13], v[12:13], v[12:13]
	v_lshlrev_b32_e32 v48, 16, v25
	v_and_b32_e32 v49, 0xffff0000, v25
	v_lshlrev_b32_e32 v50, 16, v24
	v_and_b32_e32 v51, 0xffff0000, v24
	v_mul_f32_e32 v24, v45, v45
	v_mul_f32_e32 v52, v47, v47
	v_pk_fma_f32 v[22:23], v[40:41], v[40:41], v[22:23]
	v_pk_fma_f32 v[10:11], v[10:11], v[10:11], v[12:13]
	v_pk_mul_f32 v[54:55], v[48:49], v[48:49]
	v_pk_mul_f32 v[56:57], v[50:51], v[50:51]
	v_pk_fma_f32 v[24:25], v[44:45], v[44:45], v[24:25] op_sel_hi:[1,1,0]
	v_pk_fma_f32 v[52:53], v[46:47], v[46:47], v[52:53] op_sel_hi:[1,1,0]
	v_pk_add_f32 v[12:13], v[22:23], v[22:23] op_sel:[0,1] op_sel_hi:[1,0]
	v_pk_add_f32 v[10:11], v[10:11], v[10:11] op_sel:[0,1] op_sel_hi:[1,0]
	v_mov_b32_e32 v53, v54
	v_mov_b32_e32 v25, v55
	v_mov_b32_e32 v13, v57
	v_mov_b32_e32 v11, v56
	v_pk_add_f32 v[22:23], v[52:53], v[24:25]
	v_pk_add_f32 v[10:11], v[10:11], v[12:13]
	v_lshl_add_u64 v[54:55], s[8:9], 0, v[20:21]
	v_pk_add_f32 v[10:11], v[10:11], v[22:23]
	s_nop 0
	v_add_f32_e32 v10, v10, v11
	ds_bpermute_b32 v11, v26, v10
	s_waitcnt lgkmcnt(0)
	v_add_f32_e32 v10, v10, v11
	ds_bpermute_b32 v11, v27, v10
	s_waitcnt lgkmcnt(0)
	v_add_f32_e32 v10, v10, v11
	ds_bpermute_b32 v11, v28, v10
	s_waitcnt lgkmcnt(0)
	v_add_f32_e32 v10, v10, v11
	ds_bpermute_b32 v11, v29, v10
	s_waitcnt lgkmcnt(0)
	v_add_f32_e32 v10, v10, v11
	ds_bpermute_b32 v11, v30, v10
	s_waitcnt lgkmcnt(0)
	v_add_f32_e32 v10, v10, v11
	ds_bpermute_b32 v11, v31, v10
	s_waitcnt lgkmcnt(0)
	v_add_f32_e32 v10, v10, v11
	v_fmamk_f32 v10, v10, 0x3a800000, v32
	v_rsq_f32_e32 v52, v10
	s_nop 0
	v_pk_mul_f32 v[10:11], v[52:53], v[36:37] op_sel_hi:[0,1]
	v_pk_mul_f32 v[12:13], v[52:53], v[34:35] op_sel_hi:[0,1]
	v_pk_fma_f32 v[2:3], v[2:3], v[10:11], v[6:7]
	v_pk_fma_f32 v[4:5], v[4:5], v[12:13], v[8:9]
	v_pk_mul_f32 v[22:23], v[52:53], v[40:41] op_sel_hi:[0,1]
	global_store_dwordx4 v[54:55], v[2:5], off sc1 nt
	s_nop 4
	v_mov_b64_e32 v[6:7], v[120:121]
	v_mov_b64_e32 v[8:9], v[122:123]
	v_mov_b64_e32 v[10:11], v[124:125]
	v_mov_b64_e32 v[12:13], v[126:127]
	v_pk_mul_f32 v[36:37], v[52:53], v[42:43] op_sel_hi:[0,1]
	v_lshl_add_u64 v[34:35], v[54:55], 0, s[18:19]
	v_pk_mul_f32 v[42:43], v[52:53], v[48:49] op_sel_hi:[0,1]
	s_waitcnt vmcnt(1)
	v_mov_b32_e32 v24, v6
	v_mov_b32_e32 v25, v8
	v_mov_b32_e32 v40, v10
	v_mov_b32_e32 v41, v12
	v_mov_b32_e32 v8, v7
	v_mov_b32_e32 v12, v11
	v_pk_fma_f32 v[24:25], v[24:25], v[22:23], v[40:41]
	v_pk_fma_f32 v[22:23], v[8:9], v[36:37], v[12:13]
	v_mov_b32_e32 v6, v24
	v_mov_b32_e32 v7, v22
	v_mov_b32_e32 v8, v25
	v_mov_b32_e32 v9, v23
	global_store_dwordx4 v[34:35], v[6:9], off sc1 nt
	s_nop 4
	v_mov_b64_e32 v[6:7], v[128:129]
	v_mov_b64_e32 v[8:9], v[130:131]
	v_mov_b64_e32 v[10:11], v[132:133]
	v_mov_b64_e32 v[12:13], v[134:135]
	v_pk_mul_f32 v[36:37], v[52:53], v[46:47] op_sel_hi:[0,1]
	v_pk_mul_f32 v[40:41], v[52:53], v[44:45] op_sel_hi:[0,1]
	v_lshl_add_u64 v[34:35], v[54:55], 0, s[20:21]
	v_pk_fma_f32 v[6:7], v[6:7], v[36:37], v[10:11]
	v_pk_fma_f32 v[8:9], v[8:9], v[40:41], v[12:13]
	v_pk_mul_f32 v[40:41], v[52:53], v[50:51] op_sel_hi:[0,1]
	global_store_dwordx4 v[34:35], v[6:9], off sc1 nt
	s_nop 4
	v_mov_b64_e32 v[10:11], v[136:137]
	v_mov_b64_e32 v[12:13], v[138:139]
	v_mov_b64_e32 v[34:35], v[140:141]
	v_mov_b64_e32 v[36:37], v[142:143]
	v_lshl_add_u64 v[38:39], v[54:55], 0, s[22:23]
	v_pk_fma_f32 v[10:11], v[40:41], v[10:11], v[34:35]
	v_pk_fma_f32 v[12:13], v[42:43], v[12:13], v[36:37]
	s_nop 0
	global_store_dwordx4 v[38:39], v[10:13], off sc1 nt
	s_nop 4
	s_cbranch_vccnz .LBB0_1119
; __device__ __forceinline__ unsigned cvtpk(float lo, float hi) { typedef __bf16 bf2 __attribute__((ext_vector_type(2))); f32x2 v = {lo, hi}; bf2 b = __builtin_convertvector(v, bf2); return __builtin_bit_cast(unsigned, b); }
; __device__ __forceinline__ void resnorm_rows(const float* hin, const bf16_t* tmp, const float* g1, float* hout, const float* g2, bf16_t* xn, int gw, int NGW, int lane) {
;     ...
;         if (g2) {
;             const float r2 = __builtin_amdgcn_rsqf(wave_sum(s2) * (1.f / DMODEL) + EPSN);
;             u32x2* o = (u32x2*)(xn + (size_t)row * DMODEL) + lane;
; #pragma unroll
;             for (int j = 0; j < 4; ++j) { const f32x4 gg = ((const f32x4*)g2)[lane + 64 * j]; u32x2 w; w.x = cvtpk(t[j][0] * r2 * gg[0], t[j][1] * r2 * gg[1]); w.y = cvtpk(t[j][2] * r2 * gg[2], t[j][3] * r2 * gg[3]); o[64 * j] = w; }
	v_mov_b64_e32 v[34:35], v[144:145]
	v_mov_b64_e32 v[36:37], v[146:147]
	v_mov_b32_e32 v40, v3
	v_mov_b32_e32 v41, v5
	v_mov_b32_e32 v38, v2
	v_mov_b32_e32 v39, v4
	v_pk_mul_f32 v[42:43], v[22:23], v[22:23]
	v_pk_mul_f32 v[40:41], v[40:41], v[40:41]
	v_mul_f32_e32 v44, v8, v8
	v_mul_f32_e32 v50, v6, v6
	v_pk_fma_f32 v[42:43], v[24:25], v[24:25], v[42:43]
	v_pk_fma_f32 v[38:39], v[38:39], v[38:39], v[40:41]
	v_pk_mul_f32 v[46:47], v[10:11], v[10:11]
	v_pk_mul_f32 v[48:49], v[12:13], v[12:13]
	v_pk_fma_f32 v[44:45], v[8:9], v[8:9], v[44:45] op_sel_hi:[1,1,0]
	v_pk_fma_f32 v[50:51], v[6:7], v[6:7], v[50:51] op_sel_hi:[1,1,0]
	v_pk_add_f32 v[40:41], v[42:43], v[42:43] op_sel_hi:[0,1]
	v_pk_add_f32 v[38:39], v[38:39], v[38:39] op_sel_hi:[0,1]
	v_mov_b32_e32 v50, v46
	v_mov_b32_e32 v44, v47
	v_mov_b32_e32 v40, v49
	v_mov_b32_e32 v38, v48
	v_pk_add_f32 v[42:43], v[50:51], v[44:45]
	v_pk_add_f32 v[38:39], v[38:39], v[40:41]
	s_nop 0
	v_pk_add_f32 v[38:39], v[42:43], v[38:39]
	s_nop 0
	v_add_f32_e32 v33, v38, v39
	ds_bpermute_b32 v38, v26, v33
	s_waitcnt lgkmcnt(0)
	v_add_f32_e32 v33, v33, v38
	ds_bpermute_b32 v38, v27, v33
	s_waitcnt lgkmcnt(0)
	v_add_f32_e32 v33, v33, v38
	ds_bpermute_b32 v38, v28, v33
	s_waitcnt lgkmcnt(0)
	v_add_f32_e32 v33, v33, v38
	ds_bpermute_b32 v38, v29, v33
	s_waitcnt lgkmcnt(0)
	v_add_f32_e32 v33, v33, v38
	ds_bpermute_b32 v38, v30, v33
	s_waitcnt lgkmcnt(0)
	v_add_f32_e32 v33, v33, v38
	ds_bpermute_b32 v38, v31, v33
	s_waitcnt lgkmcnt(0)
	v_add_f32_e32 v33, v33, v38
	v_fmamk_f32 v33, v33, 0x3a800000, v32
	v_rsq_f32_e32 v38, v33
	s_nop 0
	v_pk_mul_f32 v[2:3], v[2:3], v[38:39] op_sel_hi:[1,0]
	v_pk_mul_f32 v[4:5], v[4:5], v[38:39] op_sel_hi:[1,0]
	v_pk_mul_f32 v[6:7], v[6:7], v[38:39] op_sel_hi:[1,0]
	v_pk_mul_f32 v[8:9], v[8:9], v[38:39] op_sel_hi:[1,0]
	v_pk_mul_f32 v[2:3], v[34:35], v[2:3]
	v_pk_mul_f32 v[4:5], v[36:37], v[4:5]
	v_cvt_pk_bf16_f32 v2, v2, v3
	v_cvt_pk_bf16_f32 v3, v4, v5
	global_store_dwordx2 v[18:19], v[2:3], off offset:-1536
	v_mov_b64_e32 v[2:3], v[148:149]
	v_mov_b64_e32 v[4:5], v[150:151]
	v_mov_b32_e32 v34, v24
	v_mov_b32_e32 v35, v22
	v_mov_b32_e32 v22, v25
	v_pk_mul_f32 v[24:25], v[34:35], v[38:39] op_sel_hi:[1,0]
	v_pk_mul_f32 v[22:23], v[22:23], v[38:39] op_sel_hi:[1,0]
	v_pk_mul_f32 v[2:3], v[2:3], v[24:25]
	v_pk_mul_f32 v[4:5], v[4:5], v[22:23]
	v_cvt_pk_bf16_f32 v2, v2, v3
	v_cvt_pk_bf16_f32 v3, v4, v5
	global_store_dwordx2 v[18:19], v[2:3], off offset:-1024
	v_mov_b64_e32 v[2:3], v[152:153]
	v_mov_b64_e32 v[4:5], v[154:155]
	v_pk_mul_f32 v[2:3], v[6:7], v[2:3]
	v_pk_mul_f32 v[4:5], v[8:9], v[4:5]
	v_cvt_pk_bf16_f32 v2, v2, v3
	v_cvt_pk_bf16_f32 v3, v4, v5
	global_store_dwordx2 v[18:19], v[2:3], off offset:-512
	v_mov_b64_e32 v[2:3], v[156:157]
	v_mov_b64_e32 v[4:5], v[158:159]
	v_pk_mul_f32 v[6:7], v[10:11], v[38:39] op_sel_hi:[1,0]
	v_pk_mul_f32 v[8:9], v[12:13], v[38:39] op_sel_hi:[1,0]
	v_pk_mul_f32 v[2:3], v[6:7], v[2:3]
	v_pk_mul_f32 v[4:5], v[8:9], v[4:5]
	v_cvt_pk_bf16_f32 v2, v2, v3
	v_cvt_pk_bf16_f32 v3, v4, v5
	global_store_dwordx2 v[18:19], v[2:3], off
	s_branch .LBB0_1119

; __device__ __forceinline__ void resnorm_rows(const float* hin, const bf16_t* tmp, const float* g1, float* hout, const float* g2, bf16_t* xn, int gw, int NGW, int lane) {
;     ...
;         const u32x2* tr = (const u32x2*)(tmp + (size_t)row * DMODEL) + lane; f32x4 t[4]; float ss = 0.f;
; #pragma unroll
;         for (int j = 0; j < 4; ++j) { const u32x2 w = __builtin_nontemporal_load(tr + 64 * j); t[j] = (f32x4){bflo(w.x), bfhi(w.x), bflo(w.y), bfhi(w.y)}; ss += (t[j][0] * t[j][0] + t[j][1] * t[j][1]) + (t[j][2] * t[j][2] + t[j][3] * t[j][3]); }
;         const float rs = __builtin_amdgcn_rsqf(wave_sum(ss) * (1.f / DMODEL) + EPSN);
.Lrn_nopf_ph10:
	v_lshlrev_b32_e32 v45, 16, v37
	v_and_b32_e32 v47, 0xffff0000, v37
	v_and_b32_e32 v46, 0xffff0000, v36
	v_lshlrev_b32_e32 v50, 16, v39
	v_and_b32_e32 v51, 0xffff0000, v39
	v_and_b32_e32 v37, 0xffff0000, v40
	v_and_b32_e32 v39, 0xffff0000, v41
	v_lshlrev_b32_e32 v44, 16, v36
	v_lshlrev_b32_e32 v48, 16, v38
	v_and_b32_e32 v49, 0xffff0000, v38
	v_lshlrev_b32_e32 v36, 16, v40
	v_lshlrev_b32_e32 v38, 16, v41
	v_pk_mul_f32 v[40:41], v[46:47], v[46:47]
	v_mul_f32_e32 v60, v37, v37
	v_mul_f32_e32 v62, v39, v39
	v_lshlrev_b32_e32 v52, 16, v42
	v_and_b32_e32 v55, 0xffff0000, v42
	v_and_b32_e32 v54, s0, v42
	v_lshlrev_b32_e32 v56, 16, v43
	v_and_b32_e32 v57, 0xffff0000, v43
	v_mul_f32_e32 v42, v49, v49
	v_mul_f32_e32 v58, v51, v51
	v_pk_fma_f32 v[40:41], v[44:45], v[44:45], v[40:41]
	v_pk_fma_f32 v[60:61], v[36:37], v[36:37], v[60:61] op_sel_hi:[1,1,0]
	v_pk_fma_f32 v[62:63], v[38:39], v[38:39], v[62:63] op_sel_hi:[1,1,0]
	v_pk_mul_f32 v[64:65], v[54:55], v[54:55]
	v_pk_mul_f32 v[66:67], v[56:57], v[56:57]
	v_pk_fma_f32 v[42:43], v[48:49], v[48:49], v[42:43] op_sel_hi:[1,1,0]
	v_pk_fma_f32 v[58:59], v[50:51], v[50:51], v[58:59] op_sel_hi:[1,1,0]
	v_pk_add_f32 v[40:41], v[40:41], v[40:41] op_sel:[0,1] op_sel_hi:[1,0]
	v_pk_add_f32 v[60:61], v[60:61], v[62:63]
	v_mov_b32_e32 v43, v66
	v_mov_b32_e32 v59, v67
	v_mul_f32_e32 v61, v52, v52
	v_mov_b32_e32 v41, v65
	v_pk_add_f32 v[42:43], v[42:43], v[58:59]
	v_pk_add_f32 v[40:41], v[60:61], v[40:41]
	v_mov_b32_e32 v53, v55
	v_pk_add_f32 v[40:41], v[40:41], v[42:43]
	v_mov_b32_e32 v42, v44
	v_add_f32_e32 v25, v40, v41
	ds_bpermute_b32 v35, v19, v25
	v_mov_b32_e32 v43, v46
	v_mov_b32_e32 v46, v45
	v_lshl_add_u64 v[40:41], v[16:17], 0, s[16:17]
	s_waitcnt lgkmcnt(0)
	v_add_f32_e32 v25, v25, v35
	ds_bpermute_b32 v35, v20, v25
	s_waitcnt lgkmcnt(0)
	v_add_f32_e32 v25, v25, v35
	ds_bpermute_b32 v35, v21, v25
	s_waitcnt lgkmcnt(0)
	v_add_f32_e32 v25, v25, v35
	ds_bpermute_b32 v35, v22, v25
	s_waitcnt lgkmcnt(0)
	v_add_f32_e32 v25, v25, v35
	ds_bpermute_b32 v35, v23, v25
	s_waitcnt lgkmcnt(0)
	v_add_f32_e32 v25, v25, v35
	ds_bpermute_b32 v35, v24, v25
	s_waitcnt lgkmcnt(0)
; __device__ __forceinline__ unsigned cvtpk(float lo, float hi) { typedef __bf16 bf2 __attribute__((ext_vector_type(2))); f32x2 v = {lo, hi}; bf2 b = __builtin_convertvector(v, bf2); return __builtin_bit_cast(unsigned, b); }
; __device__ __forceinline__ void st16_wt(void* p, u32x4 v) { asm volatile("global_store_dwordx4 %0, %1, off sc1\n\ts_nop 4" :: "v"(p), "v"(v) : "memory"); }
; __device__ __forceinline__ void resnorm_rows(const float* hin, const bf16_t* tmp, const float* g1, float* hout, const float* g2, bf16_t* xn, int gw, int NGW, int lane) {
;     ...
;         const float rs = __builtin_amdgcn_rsqf(wave_sum(ss) * (1.f / DMODEL) + EPSN);
;         const f32x4* hr = (const f32x4*)(hin + (size_t)row * DMODEL) + lane; f32x4* ho = (f32x4*)(hout + (size_t)row * DMODEL) + lane; float s2 = 0.f;
; #pragma unroll
;         for (int j = 0; j < 4; ++j) { const f32x4 gg = ((const f32x4*)g1)[lane + 64 * j]; f32x4 h = __builtin_nontemporal_load(hr + 64 * j);
;             h[0] += t[j][0] * rs * gg[0]; h[1] += t[j][1] * rs * gg[1]; h[2] += t[j][2] * rs * gg[2]; h[3] += t[j][3] * rs * gg[3];
;             st16_wt(ho + 64 * j, __builtin_bit_cast(u32x4, h)); t[j] = h; s2 += (h[0] * h[0] + h[1] * h[1]) + (h[2] * h[2] + h[3] * h[3]); }
;         if (g2) {
;             const float r2 = __builtin_amdgcn_rsqf(wave_sum(s2) * (1.f / DMODEL) + EPSN);
;             u32x2* o = (u32x2*)(xn + (size_t)row * DMODEL) + lane;
; #pragma unroll
;             for (int j = 0; j < 4; ++j) { const f32x4 gg = ((const f32x4*)g2)[lane + 64 * j]; u32x2 w; w.x = cvtpk(t[j][0] * r2 * gg[0], t[j][1] * r2 * gg[1]); w.y = cvtpk(t[j][2] * r2 * gg[2], t[j][3] * r2 * gg[3]); o[64 * j] = w; }
	v_add_f32_e32 v25, v25, v35
	v_fmamk_f32 v25, v25, 0x3a800000, v5
	v_rsq_f32_e32 v54, v25
	s_nop 0
	v_pk_mul_f32 v[36:37], v[54:55], v[36:37] op_sel_hi:[0,1]
	v_pk_mul_f32 v[38:39], v[54:55], v[38:39] op_sel_hi:[0,1]
	v_pk_fma_f32 v[26:27], v[26:27], v[36:37], v[30:31]
	v_pk_fma_f32 v[28:29], v[28:29], v[38:39], v[32:33]
	v_pk_mul_f32 v[42:43], v[54:55], v[42:43] op_sel_hi:[0,1]
	global_store_dwordx4 v[16:17], v[26:29], off sc1 nt
	s_nop 4
	v_mov_b64_e32 v[30:31], v[120:121]
	v_mov_b64_e32 v[32:33], v[122:123]
	v_mov_b64_e32 v[36:37], v[124:125]
	v_mov_b64_e32 v[38:39], v[126:127]
	v_pk_mul_f32 v[44:45], v[54:55], v[46:47] op_sel_hi:[0,1]
	v_pk_mul_f32 v[46:47], v[54:55], v[48:49] op_sel_hi:[0,1]
	v_pk_mul_f32 v[48:49], v[54:55], v[50:51] op_sel_hi:[0,1]
	v_pk_mul_f32 v[50:51], v[54:55], v[52:53] op_sel_hi:[0,1]
	v_pk_mul_f32 v[52:53], v[54:55], v[56:57] op_sel_hi:[0,1]
	v_pk_fma_f32 v[30:31], v[30:31], v[42:43], v[36:37]
	v_pk_fma_f32 v[32:33], v[32:33], v[44:45], v[38:39]
	v_lshl_add_u64 v[44:45], v[16:17], 0, s[18:19]
	global_store_dwordx4 v[40:41], v[30:33], off sc1 nt
	s_nop 4
	v_mov_b64_e32 v[36:37], v[128:129]
	v_mov_b64_e32 v[38:39], v[130:131]
	v_mov_b64_e32 v[40:41], v[132:133]
	v_mov_b64_e32 v[42:43], v[134:135]
	v_pk_fma_f32 v[36:37], v[36:37], v[46:47], v[40:41]
	v_pk_fma_f32 v[38:39], v[38:39], v[48:49], v[42:43]
	v_lshl_add_u64 v[48:49], v[16:17], 0, s[20:21]
	global_store_dwordx4 v[44:45], v[36:39], off sc1 nt
	s_nop 4
	v_mov_b64_e32 v[40:41], v[136:137]
	v_mov_b64_e32 v[42:43], v[138:139]
	v_mov_b64_e32 v[44:45], v[140:141]
	v_mov_b64_e32 v[46:47], v[142:143]
	v_lshl_add_u64 v[16:17], v[16:17], 0, s[10:11]
	v_pk_fma_f32 v[40:41], v[50:51], v[40:41], v[44:45]
	v_pk_fma_f32 v[42:43], v[52:53], v[42:43], v[46:47]
	v_mov_b32_e32 v50, v27
	global_store_dwordx4 v[48:49], v[40:43], off sc1 nt
	s_nop 4
	v_mov_b64_e32 v[44:45], v[144:145]
	v_mov_b64_e32 v[46:47], v[146:147]
	v_mov_b32_e32 v51, v29
	v_mov_b32_e32 v48, v26
	v_mov_b32_e32 v49, v28
	v_pk_mul_f32 v[50:51], v[50:51], v[50:51]
	v_mov_b32_e32 v52, v31
	v_mov_b32_e32 v53, v33
	v_pk_fma_f32 v[48:49], v[48:49], v[48:49], v[50:51]
	v_mov_b32_e32 v50, v30
	v_mov_b32_e32 v51, v32
	v_pk_mul_f32 v[52:53], v[52:53], v[52:53]
	v_pk_add_f32 v[48:49], v[48:49], v[48:49] op_sel_hi:[0,1]
	v_pk_fma_f32 v[50:51], v[50:51], v[50:51], v[52:53]
	v_mul_f32_e32 v48, v36, v36
	v_pk_add_f32 v[50:51], v[50:51], v[50:51] op_sel_hi:[0,1]
	v_mul_f32_e32 v50, v38, v38
	v_pk_fma_f32 v[52:53], v[36:37], v[36:37], v[48:49] op_sel_hi:[1,1,0]
	v_pk_fma_f32 v[54:55], v[38:39], v[38:39], v[50:51] op_sel_hi:[1,1,0]
	v_pk_mul_f32 v[56:57], v[40:41], v[40:41]
	v_pk_mul_f32 v[58:59], v[42:43], v[42:43]
	v_mov_b32_e32 v52, v56
	v_mov_b32_e32 v54, v57
	v_mov_b32_e32 v48, v58
	v_mov_b32_e32 v50, v59
	v_pk_add_f32 v[52:53], v[52:53], v[54:55]
	v_pk_add_f32 v[48:49], v[48:49], v[50:51]
	s_nop 0
	v_pk_add_f32 v[48:49], v[52:53], v[48:49]
	s_nop 0
	v_add_f32_e32 v25, v48, v49
	ds_bpermute_b32 v35, v19, v25
	s_waitcnt lgkmcnt(0)
	v_add_f32_e32 v25, v25, v35
	ds_bpermute_b32 v35, v20, v25
	s_waitcnt lgkmcnt(0)
	v_add_f32_e32 v25, v25, v35
	ds_bpermute_b32 v35, v21, v25
	s_waitcnt lgkmcnt(0)
	v_add_f32_e32 v25, v25, v35
	ds_bpermute_b32 v35, v22, v25
	s_waitcnt lgkmcnt(0)
	v_add_f32_e32 v25, v25, v35
	ds_bpermute_b32 v35, v23, v25
	s_waitcnt lgkmcnt(0)
	v_add_f32_e32 v25, v25, v35
	ds_bpermute_b32 v35, v24, v25
	s_waitcnt lgkmcnt(0)
	v_add_f32_e32 v25, v25, v35
	v_fmamk_f32 v25, v25, 0x3a800000, v5
	v_rsq_f32_e32 v48, v25
	s_nop 0
	v_pk_mul_f32 v[26:27], v[26:27], v[48:49] op_sel_hi:[1,0]
	v_pk_mul_f32 v[28:29], v[28:29], v[48:49] op_sel_hi:[1,0]
	v_pk_mul_f32 v[30:31], v[30:31], v[48:49] op_sel_hi:[1,0]
	v_pk_mul_f32 v[32:33], v[32:33], v[48:49] op_sel_hi:[1,0]
	v_pk_mul_f32 v[26:27], v[44:45], v[26:27]
	v_pk_mul_f32 v[28:29], v[46:47], v[28:29]
	v_cvt_pk_bf16_f32 v26, v26, v27
	v_cvt_pk_bf16_f32 v27, v28, v29
	global_store_dwordx2 v[14:15], v[26:27], off offset:-1024
	v_mov_b64_e32 v[26:27], v[148:149]
	v_mov_b64_e32 v[28:29], v[150:151]
	v_pk_mul_f32 v[26:27], v[26:27], v[30:31]
	v_pk_mul_f32 v[28:29], v[28:29], v[32:33]
	v_cvt_pk_bf16_f32 v26, v26, v27
	v_cvt_pk_bf16_f32 v27, v28, v29
	global_store_dwordx2 v[14:15], v[26:27], off offset:-512
	v_mov_b64_e32 v[26:27], v[152:153]
	v_mov_b64_e32 v[28:29], v[154:155]
	v_pk_mul_f32 v[30:31], v[36:37], v[48:49] op_sel_hi:[1,0]
	v_pk_mul_f32 v[32:33], v[38:39], v[48:49] op_sel_hi:[1,0]
	v_pk_mul_f32 v[26:27], v[26:27], v[30:31]
	v_pk_mul_f32 v[28:29], v[28:29], v[32:33]
	v_cvt_pk_bf16_f32 v26, v26, v27
	v_cvt_pk_bf16_f32 v27, v28, v29
	global_store_dwordx2 v[14:15], v[26:27], off
	v_mov_b64_e32 v[26:27], v[156:157]
	v_mov_b64_e32 v[28:29], v[158:159]
	v_pk_mul_f32 v[30:31], v[40:41], v[48:49] op_sel_hi:[1,0]
	v_pk_mul_f32 v[32:33], v[42:43], v[48:49] op_sel_hi:[1,0]
	v_pk_mul_f32 v[26:27], v[26:27], v[30:31]
	v_pk_mul_f32 v[28:29], v[28:29], v[32:33]
	v_cvt_pk_bf16_f32 v26, v26, v27
	v_cvt_pk_bf16_f32 v27, v28, v29
	global_store_dwordx2 v[14:15], v[26:27], off offset:512
	v_lshl_add_u64 v[14:15], v[14:15], 0, s[8:9]
	s_cbranch_scc1 .LBB0_1441

; __device__ __forceinline__ void resnorm_rows(const float* hin, const bf16_t* tmp, const float* g1, float* hout, const float* g2, bf16_t* xn, int gw, int NGW, int lane) {
;     ...
;         const u32x2* tr = (const u32x2*)(tmp + (size_t)row * DMODEL) + lane; f32x4 t[4]; float ss = 0.f;
; #pragma unroll
;         for (int j = 0; j < 4; ++j) { const u32x2 w = __builtin_nontemporal_load(tr + 64 * j); t[j] = (f32x4){bflo(w.x), bfhi(w.x), bflo(w.y), bfhi(w.y)}; ss += (t[j][0] * t[j][0] + t[j][1] * t[j][1]) + (t[j][2] * t[j][2] + t[j][3] * t[j][3]); }
;         const float rs = __builtin_amdgcn_rsqf(wave_sum(ss) * (1.f / DMODEL) + EPSN);
.Lrn_nopf_ph17:
	v_lshlrev_b32_e32 v49, 16, v41
	v_and_b32_e32 v51, 0xffff0000, v41
	v_and_b32_e32 v50, 0xffff0000, v40
	v_and_b32_e32 v39, 0xffff0000, v44
	v_and_b32_e32 v41, 0xffff0000, v45
	v_lshlrev_b32_e32 v48, 16, v40
	v_lshlrev_b32_e32 v52, 16, v42
	v_and_b32_e32 v53, 0xffff0000, v42
	v_lshlrev_b32_e32 v54, 16, v43
	v_and_b32_e32 v55, 0xffff0000, v43
	v_lshlrev_b32_e32 v38, 16, v44
	v_lshlrev_b32_e32 v40, 16, v45
	v_pk_mul_f32 v[42:43], v[50:51], v[50:51]
	v_mul_f32_e32 v62, v39, v39
	v_mul_f32_e32 v64, v41, v41
	v_lshlrev_b32_e32 v56, 16, v46
	v_and_b32_e32 v59, 0xffff0000, v46
	v_and_b32_e32 v58, s0, v46
	v_lshlrev_b32_e32 v60, 16, v47
	v_and_b32_e32 v61, 0xffff0000, v47
	v_mul_f32_e32 v44, v53, v53
	v_mul_f32_e32 v46, v55, v55
	v_pk_fma_f32 v[42:43], v[48:49], v[48:49], v[42:43]
	v_pk_fma_f32 v[62:63], v[38:39], v[38:39], v[62:63] op_sel_hi:[1,1,0]
	v_pk_fma_f32 v[64:65], v[40:41], v[40:41], v[64:65] op_sel_hi:[1,1,0]
	v_pk_mul_f32 v[66:67], v[58:59], v[58:59]
	v_pk_mul_f32 v[68:69], v[60:61], v[60:61]
	v_pk_fma_f32 v[44:45], v[52:53], v[52:53], v[44:45] op_sel_hi:[1,1,0]
	v_pk_fma_f32 v[46:47], v[54:55], v[54:55], v[46:47] op_sel_hi:[1,1,0]
	v_pk_add_f32 v[42:43], v[42:43], v[42:43] op_sel:[0,1] op_sel_hi:[1,0]
	v_pk_add_f32 v[62:63], v[62:63], v[64:65]
	v_mov_b32_e32 v45, v68
	v_mov_b32_e32 v47, v69
	v_mul_f32_e32 v63, v56, v56
	v_mov_b32_e32 v43, v67
	v_pk_add_f32 v[44:45], v[44:45], v[46:47]
	v_pk_add_f32 v[42:43], v[62:63], v[42:43]
	v_mov_b32_e32 v57, v59
	v_pk_add_f32 v[42:43], v[42:43], v[44:45]
	v_mov_b32_e32 v44, v48
	v_add_f32_e32 v29, v42, v43
	ds_bpermute_b32 v42, v22, v29
	v_mov_b32_e32 v45, v50
	v_mov_b32_e32 v50, v49
	s_waitcnt lgkmcnt(0)
	v_add_f32_e32 v29, v29, v42
	ds_bpermute_b32 v42, v23, v29
	s_waitcnt lgkmcnt(0)
	v_add_f32_e32 v29, v29, v42
	ds_bpermute_b32 v42, v24, v29
	s_waitcnt lgkmcnt(0)
	v_add_f32_e32 v29, v29, v42
	ds_bpermute_b32 v42, v25, v29
	s_waitcnt lgkmcnt(0)
	v_add_f32_e32 v29, v29, v42
	ds_bpermute_b32 v42, v26, v29
	s_waitcnt lgkmcnt(0)
	v_add_f32_e32 v29, v29, v42
	ds_bpermute_b32 v42, v27, v29
	s_waitcnt lgkmcnt(0)
; __device__ __forceinline__ unsigned cvtpk(float lo, float hi) { typedef __bf16 bf2 __attribute__((ext_vector_type(2))); f32x2 v = {lo, hi}; bf2 b = __builtin_convertvector(v, bf2); return __builtin_bit_cast(unsigned, b); }
; __device__ __forceinline__ void st16_wt(void* p, u32x4 v) { asm volatile("global_store_dwordx4 %0, %1, off sc1\n\ts_nop 4" :: "v"(p), "v"(v) : "memory"); }
; __device__ __forceinline__ void resnorm_rows(const float* hin, const bf16_t* tmp, const float* g1, float* hout, const float* g2, bf16_t* xn, int gw, int NGW, int lane) {
;     ...
;         const float rs = __builtin_amdgcn_rsqf(wave_sum(ss) * (1.f / DMODEL) + EPSN);
;         const f32x4* hr = (const f32x4*)(hin + (size_t)row * DMODEL) + lane; f32x4* ho = (f32x4*)(hout + (size_t)row * DMODEL) + lane; float s2 = 0.f;
; #pragma unroll
;         for (int j = 0; j < 4; ++j) { const f32x4 gg = ((const f32x4*)g1)[lane + 64 * j]; f32x4 h = __builtin_nontemporal_load(hr + 64 * j);
;             h[0] += t[j][0] * rs * gg[0]; h[1] += t[j][1] * rs * gg[1]; h[2] += t[j][2] * rs * gg[2]; h[3] += t[j][3] * rs * gg[3];
;             st16_wt(ho + 64 * j, __builtin_bit_cast(u32x4, h)); t[j] = h; s2 += (h[0] * h[0] + h[1] * h[1]) + (h[2] * h[2] + h[3] * h[3]); }
;         if (g2) {
;             const float r2 = __builtin_amdgcn_rsqf(wave_sum(s2) * (1.f / DMODEL) + EPSN);
;             u32x2* o = (u32x2*)(xn + (size_t)row * DMODEL) + lane;
; #pragma unroll
;             for (int j = 0; j < 4; ++j) { const f32x4 gg = ((const f32x4*)g2)[lane + 64 * j]; u32x2 w; w.x = cvtpk(t[j][0] * r2 * gg[0], t[j][1] * r2 * gg[1]); w.y = cvtpk(t[j][2] * r2 * gg[2], t[j][3] * r2 * gg[3]); o[64 * j] = w; }
	v_add_f32_e32 v29, v29, v42
	v_fmamk_f32 v29, v29, 0x3a800000, v28
	v_rsq_f32_e32 v58, v29
	v_lshl_add_u64 v[42:43], v[20:21], 0, s[8:9]
	v_pk_mul_f32 v[38:39], v[58:59], v[38:39] op_sel_hi:[0,1]
	v_pk_mul_f32 v[40:41], v[58:59], v[40:41] op_sel_hi:[0,1]
	v_pk_fma_f32 v[30:31], v[30:31], v[38:39], v[34:35]
	v_pk_fma_f32 v[32:33], v[32:33], v[40:41], v[36:37]
	v_pk_mul_f32 v[44:45], v[58:59], v[44:45] op_sel_hi:[0,1]
	global_store_dwordx4 v[20:21], v[30:33], off sc1 nt
	s_nop 4
	v_mov_b64_e32 v[34:35], v[120:121]
	v_mov_b64_e32 v[36:37], v[122:123]
	v_mov_b64_e32 v[38:39], v[124:125]
	v_mov_b64_e32 v[40:41], v[126:127]
	v_pk_mul_f32 v[46:47], v[58:59], v[50:51] op_sel_hi:[0,1]
	v_pk_mul_f32 v[48:49], v[58:59], v[52:53] op_sel_hi:[0,1]
	v_pk_mul_f32 v[50:51], v[58:59], v[54:55] op_sel_hi:[0,1]
	v_pk_mul_f32 v[52:53], v[58:59], v[56:57] op_sel_hi:[0,1]
	v_pk_mul_f32 v[54:55], v[58:59], v[60:61] op_sel_hi:[0,1]
	v_pk_fma_f32 v[34:35], v[34:35], v[44:45], v[38:39]
	v_pk_fma_f32 v[36:37], v[36:37], v[46:47], v[40:41]
	v_lshl_add_u64 v[46:47], v[20:21], 0, s[10:11]
	global_store_dwordx4 v[42:43], v[34:37], off sc1 nt
	s_nop 4
	v_mov_b64_e32 v[38:39], v[128:129]
	v_mov_b64_e32 v[40:41], v[130:131]
	v_mov_b64_e32 v[42:43], v[132:133]
	v_mov_b64_e32 v[44:45], v[134:135]
	v_pk_fma_f32 v[38:39], v[38:39], v[48:49], v[42:43]
	v_pk_fma_f32 v[40:41], v[40:41], v[50:51], v[44:45]
	v_lshl_add_u64 v[50:51], v[20:21], 0, s[16:17]
	global_store_dwordx4 v[46:47], v[38:41], off sc1 nt
	s_nop 4
	v_mov_b64_e32 v[42:43], v[136:137]
	v_mov_b64_e32 v[44:45], v[138:139]
	v_mov_b64_e32 v[46:47], v[140:141]
	v_mov_b64_e32 v[48:49], v[142:143]
	v_lshl_add_u64 v[20:21], v[20:21], 0, s[4:5]
	v_pk_fma_f32 v[42:43], v[52:53], v[42:43], v[46:47]
	v_pk_fma_f32 v[44:45], v[54:55], v[44:45], v[48:49]
	v_mov_b32_e32 v52, v31
	global_store_dwordx4 v[50:51], v[42:45], off sc1 nt
	s_nop 4
	v_mov_b64_e32 v[46:47], v[144:145]
	v_mov_b64_e32 v[48:49], v[146:147]
	v_mov_b32_e32 v53, v33
	v_mov_b32_e32 v50, v30
	v_mov_b32_e32 v51, v32
	v_pk_mul_f32 v[52:53], v[52:53], v[52:53]
	v_mov_b32_e32 v54, v35
	v_mov_b32_e32 v55, v37
	v_pk_fma_f32 v[50:51], v[50:51], v[50:51], v[52:53]
	v_mov_b32_e32 v52, v34
	v_mov_b32_e32 v53, v36
	v_pk_mul_f32 v[54:55], v[54:55], v[54:55]
	v_pk_add_f32 v[50:51], v[50:51], v[50:51] op_sel_hi:[0,1]
	v_pk_fma_f32 v[52:53], v[52:53], v[52:53], v[54:55]
	v_mul_f32_e32 v50, v38, v38
	v_pk_add_f32 v[52:53], v[52:53], v[52:53] op_sel_hi:[0,1]
	v_mul_f32_e32 v52, v40, v40
	v_pk_fma_f32 v[54:55], v[38:39], v[38:39], v[50:51] op_sel_hi:[1,1,0]
	v_pk_fma_f32 v[56:57], v[40:41], v[40:41], v[52:53] op_sel_hi:[1,1,0]
	v_pk_mul_f32 v[58:59], v[42:43], v[42:43]
	v_pk_mul_f32 v[60:61], v[44:45], v[44:45]
	v_mov_b32_e32 v54, v58
	v_mov_b32_e32 v56, v59
	v_mov_b32_e32 v50, v60
	v_mov_b32_e32 v52, v61
	v_pk_add_f32 v[54:55], v[54:55], v[56:57]
	v_pk_add_f32 v[50:51], v[50:51], v[52:53]
	s_nop 0
	v_pk_add_f32 v[50:51], v[54:55], v[50:51]
	s_nop 0
	v_add_f32_e32 v29, v50, v51
	ds_bpermute_b32 v50, v22, v29
	s_waitcnt lgkmcnt(0)
	v_add_f32_e32 v29, v29, v50
	ds_bpermute_b32 v50, v23, v29
	s_waitcnt lgkmcnt(0)
	v_add_f32_e32 v29, v29, v50
	ds_bpermute_b32 v50, v24, v29
	s_waitcnt lgkmcnt(0)
	v_add_f32_e32 v29, v29, v50
	ds_bpermute_b32 v50, v25, v29
	s_waitcnt lgkmcnt(0)
	v_add_f32_e32 v29, v29, v50
	ds_bpermute_b32 v50, v26, v29
	s_waitcnt lgkmcnt(0)
	v_add_f32_e32 v29, v29, v50
	ds_bpermute_b32 v50, v27, v29
	s_waitcnt lgkmcnt(0)
	v_add_f32_e32 v29, v29, v50
	v_fmamk_f32 v29, v29, 0x3a800000, v28
	v_rsq_f32_e32 v50, v29
	s_nop 0
	v_pk_mul_f32 v[30:31], v[30:31], v[50:51] op_sel_hi:[1,0]
	v_pk_mul_f32 v[32:33], v[32:33], v[50:51] op_sel_hi:[1,0]
	v_pk_mul_f32 v[34:35], v[34:35], v[50:51] op_sel_hi:[1,0]
	v_pk_mul_f32 v[36:37], v[36:37], v[50:51] op_sel_hi:[1,0]
	v_pk_mul_f32 v[30:31], v[46:47], v[30:31]
	v_pk_mul_f32 v[32:33], v[48:49], v[32:33]
	v_cvt_pk_bf16_f32 v30, v30, v31
	v_cvt_pk_bf16_f32 v31, v32, v33
	global_store_dwordx2 v[18:19], v[30:31], off offset:-1536
	v_mov_b64_e32 v[30:31], v[148:149]
	v_mov_b64_e32 v[32:33], v[150:151]
	v_pk_mul_f32 v[30:31], v[30:31], v[34:35]
	v_pk_mul_f32 v[32:33], v[32:33], v[36:37]
	v_cvt_pk_bf16_f32 v30, v30, v31
	v_cvt_pk_bf16_f32 v31, v32, v33
	global_store_dwordx2 v[18:19], v[30:31], off offset:-1024
	v_mov_b64_e32 v[30:31], v[152:153]
	v_mov_b64_e32 v[32:33], v[154:155]
	v_pk_mul_f32 v[34:35], v[38:39], v[50:51] op_sel_hi:[1,0]
	v_pk_mul_f32 v[36:37], v[40:41], v[50:51] op_sel_hi:[1,0]
	v_pk_mul_f32 v[30:31], v[30:31], v[34:35]
	v_pk_mul_f32 v[32:33], v[32:33], v[36:37]
	v_cvt_pk_bf16_f32 v30, v30, v31
	v_cvt_pk_bf16_f32 v31, v32, v33
	global_store_dwordx2 v[18:19], v[30:31], off offset:-512
	v_mov_b64_e32 v[30:31], v[156:157]
	v_mov_b64_e32 v[32:33], v[158:159]
	v_pk_mul_f32 v[34:35], v[42:43], v[50:51] op_sel_hi:[1,0]
	v_pk_mul_f32 v[36:37], v[44:45], v[50:51] op_sel_hi:[1,0]
	v_pk_mul_f32 v[30:31], v[30:31], v[34:35]
	v_pk_mul_f32 v[32:33], v[32:33], v[36:37]
	v_cvt_pk_bf16_f32 v30, v30, v31
	v_cvt_pk_bf16_f32 v31, v32, v33
	global_store_dwordx2 v[18:19], v[30:31], off
	v_lshl_add_u64 v[18:19], v[18:19], 0, s[6:7]
	s_cbranch_scc1 .LBB0_2547

; __device__ __forceinline__ void st16_wt(void* p, u32x4 v) { asm volatile("global_store_dwordx4 %0, %1, off sc1\n\ts_nop 4" :: "v"(p), "v"(v) : "memory"); }
; __device__ __forceinline__ void resnorm_rows(const float* hin, const bf16_t* tmp, const float* g1, float* hout, const float* g2, bf16_t* xn, int gw, int NGW, int lane) {
;     ...
;         const u32x2* tr = (const u32x2*)(tmp + (size_t)row * DMODEL) + lane; f32x4 t[4]; float ss = 0.f;
; #pragma unroll
;         for (int j = 0; j < 4; ++j) { const u32x2 w = __builtin_nontemporal_load(tr + 64 * j); t[j] = (f32x4){bflo(w.x), bfhi(w.x), bflo(w.y), bfhi(w.y)}; ss += (t[j][0] * t[j][0] + t[j][1] * t[j][1]) + (t[j][2] * t[j][2] + t[j][3] * t[j][3]); }
;         const float rs = __builtin_amdgcn_rsqf(wave_sum(ss) * (1.f / DMODEL) + EPSN);
;         const f32x4* hr = (const f32x4*)(hin + (size_t)row * DMODEL) + lane; f32x4* ho = (f32x4*)(hout + (size_t)row * DMODEL) + lane; float s2 = 0.f;
; #pragma unroll
;         for (int j = 0; j < 4; ++j) { const f32x4 gg = ((const f32x4*)g1)[lane + 64 * j]; f32x4 h = __builtin_nontemporal_load(hr + 64 * j);
;             h[0] += t[j][0] * rs * gg[0]; h[1] += t[j][1] * rs * gg[1]; h[2] += t[j][2] * rs * gg[2]; h[3] += t[j][3] * rs * gg[3];
;             st16_wt(ho + 64 * j, __builtin_bit_cast(u32x4, h)); t[j] = h; s2 += (h[0] * h[0] + h[1] * h[1]) + (h[2] * h[2] + h[3] * h[3]); }
.Lrn_nopf_ph20:
	v_lshlrev_b32_e32 v33, 16, v25
	v_lshlrev_b32_e32 v32, 16, v24
	v_and_b32_e32 v25, 0xffff0000, v25
	v_and_b32_e32 v24, 0xffff0000, v24
	v_lshlrev_b32_e32 v36, 16, v28
	v_and_b32_e32 v37, 0xffff0000, v28
	v_lshlrev_b32_e32 v28, 16, v29
	v_and_b32_e32 v29, 0xffff0000, v29
	v_lshlrev_b32_e32 v34, 16, v26
	v_and_b32_e32 v35, 0xffff0000, v26
	v_lshlrev_b32_e32 v26, 16, v27
	v_and_b32_e32 v27, 0xffff0000, v27
	v_pk_mul_f32 v[42:43], v[24:25], v[24:25]
	v_mul_f32_e32 v48, v37, v37
	v_mul_f32_e32 v50, v29, v29
	v_lshlrev_b32_e32 v38, 16, v30
	v_and_b32_e32 v41, 0xffff0000, v30
	v_and_b32_e32 v40, s0, v30
	v_lshlrev_b32_e32 v30, 16, v31
	v_and_b32_e32 v31, 0xffff0000, v31
	v_mul_f32_e32 v44, v35, v35
	v_mul_f32_e32 v46, v27, v27
	v_pk_fma_f32 v[42:43], v[32:33], v[32:33], v[42:43]
	v_pk_fma_f32 v[48:49], v[36:37], v[36:37], v[48:49] op_sel_hi:[1,1,0]
	v_pk_fma_f32 v[50:51], v[28:29], v[28:29], v[50:51] op_sel_hi:[1,1,0]
	v_pk_mul_f32 v[52:53], v[40:41], v[40:41]
	v_pk_mul_f32 v[54:55], v[30:31], v[30:31]
	v_pk_fma_f32 v[44:45], v[34:35], v[34:35], v[44:45] op_sel_hi:[1,1,0]
	v_pk_fma_f32 v[46:47], v[26:27], v[26:27], v[46:47] op_sel_hi:[1,1,0]
	v_pk_add_f32 v[42:43], v[42:43], v[42:43] op_sel:[0,1] op_sel_hi:[1,0]
	v_pk_add_f32 v[48:49], v[48:49], v[50:51]
	v_mov_b32_e32 v45, v54
	v_mov_b32_e32 v47, v55
	v_mul_f32_e32 v49, v38, v38
	v_mov_b32_e32 v43, v53
	v_pk_add_f32 v[44:45], v[44:45], v[46:47]
	v_pk_add_f32 v[42:43], v[48:49], v[42:43]
	s_nop 0
	v_pk_add_f32 v[42:43], v[42:43], v[44:45]
	s_nop 0
	v_add_f32_e32 v15, v42, v43
	ds_bpermute_b32 v39, v8, v15
	s_waitcnt lgkmcnt(0)
	v_add_f32_e32 v15, v15, v39
	ds_bpermute_b32 v39, v9, v15
	s_waitcnt lgkmcnt(0)
	v_add_f32_e32 v15, v15, v39
	ds_bpermute_b32 v39, v10, v15
	s_waitcnt lgkmcnt(0)
	v_add_f32_e32 v15, v15, v39
	ds_bpermute_b32 v39, v11, v15
	s_waitcnt lgkmcnt(0)
	v_add_f32_e32 v15, v15, v39
	ds_bpermute_b32 v39, v12, v15
	s_waitcnt lgkmcnt(0)
	v_add_f32_e32 v15, v15, v39
	ds_bpermute_b32 v39, v13, v15
	s_waitcnt lgkmcnt(0)
	v_add_f32_e32 v15, v15, v39
	v_fmamk_f32 v15, v15, 0x3a800000, v14
	v_rsq_f32_e32 v40, v15
	v_mov_b32_e32 v39, v41
	v_pk_mul_f32 v[36:37], v[40:41], v[36:37] op_sel_hi:[0,1]
	v_pk_mul_f32 v[28:29], v[40:41], v[28:29] op_sel_hi:[0,1]
	v_pk_fma_f32 v[18:19], v[18:19], v[28:29], v[22:23]
	v_pk_fma_f32 v[16:17], v[16:17], v[36:37], v[20:21]
	v_mov_b32_e32 v36, v32
	global_store_dwordx4 v[6:7], v[16:19], off sc1 nt
	s_nop 4
	v_mov_b64_e32 v[16:17], v[120:121]
	v_mov_b64_e32 v[18:19], v[122:123]
	v_mov_b64_e32 v[20:21], v[124:125]
	v_mov_b64_e32 v[22:23], v[126:127]
	v_mov_b32_e32 v37, v24
	v_mov_b32_e32 v24, v33
	v_pk_mul_f32 v[32:33], v[40:41], v[36:37] op_sel_hi:[0,1]
	v_pk_mul_f32 v[24:25], v[40:41], v[24:25] op_sel_hi:[0,1]
	v_lshl_add_u64 v[28:29], v[6:7], 0, s[4:5]
	v_pk_mul_f32 v[26:27], v[40:41], v[26:27] op_sel_hi:[0,1]
	v_pk_fma_f32 v[16:17], v[16:17], v[32:33], v[20:21]
	v_pk_fma_f32 v[18:19], v[18:19], v[24:25], v[22:23]
	v_lshl_add_u64 v[24:25], v[6:7], 0, s[6:7]
	global_store_dwordx4 v[28:29], v[16:19], off sc1 nt
	s_nop 4
	v_mov_b64_e32 v[16:17], v[128:129]
	v_mov_b64_e32 v[18:19], v[130:131]
	v_mov_b64_e32 v[20:21], v[132:133]
	v_mov_b64_e32 v[22:23], v[134:135]
	v_pk_mul_f32 v[28:29], v[40:41], v[34:35] op_sel_hi:[0,1]
	v_pk_fma_f32 v[16:17], v[16:17], v[28:29], v[20:21]
	v_pk_fma_f32 v[18:19], v[18:19], v[26:27], v[22:23]
	v_pk_mul_f32 v[26:27], v[40:41], v[30:31] op_sel_hi:[0,1]
	global_store_dwordx4 v[24:25], v[16:19], off sc1 nt
	s_nop 4
	v_mov_b64_e32 v[16:17], v[136:137]
	v_mov_b64_e32 v[18:19], v[138:139]
	v_mov_b64_e32 v[20:21], v[140:141]
	v_mov_b64_e32 v[22:23], v[142:143]
	v_pk_mul_f32 v[28:29], v[40:41], v[38:39] op_sel_hi:[0,1]
	v_lshl_add_u64 v[24:25], v[6:7], 0, s[8:9]
	v_lshl_add_u64 v[6:7], v[6:7], 0, s[2:3]
	v_pk_fma_f32 v[16:17], v[28:29], v[16:17], v[20:21]
	v_pk_fma_f32 v[18:19], v[26:27], v[18:19], v[22:23]
	s_nop 0
	global_store_dwordx4 v[24:25], v[16:19], off sc1 nt
	s_nop 4
	s_cbranch_scc1 .LBB0_2867
